# GEMM main K-loop head aligned to a 64-byte boundary
# speedup vs baseline: 1.0038x; 1.0038x over previous
; #define PG8_STAGE(bufoff, gbase, voff) do { _Pragma("unroll") for (int _i = 0; _i < 2; ++_i) \
;         __builtin_amdgcn_global_load_lds((const unsigned*)((const char*)(gbase) + (voff)[_i]), (LAS unsigned*)(lds + (bufoff) + ldsw + _i * 8192), 16, 0, 0); } while (0)
; #define PG8_LDA(dst, b, h) do { _Pragma("unroll") for (int m = 0; m < 4; ++m) _Pragma("unroll") for (int k = 0; k < 2; ++k) dst[m][k] = *(const LAS bf16x8*)(lds + PG8_SA(b, h) + aoff + m * 2048 + k * 1024); } while (0)
; #define PG8_LDB(dst, b, h) do { _Pragma("unroll") for (int n = 0; n < 2; ++n) _Pragma("unroll") for (int k = 0; k < 2; ++k) dst[n][k] = *(const LAS bf16x8*)(lds + PG8_SB(b, h) + boff + n * 2048 + k * 1024); } while (0)
; #define PG8_MMA(ai, bj, At, Bt) do { __builtin_amdgcn_s_setprio(1); _Pragma("unroll") for (int m = 0; m < 4; ++m) _Pragma("unroll") for (int n = 0; n < 2; ++n) _Pragma("unroll") for (int k = 0; k < 2; ++k) \
;         acc[ai][bj][m][n] = __builtin_amdgcn_mfma_f32_16x16x32_bf16(Bt[n][k], At[m][k], acc[ai][bj][m][n], 0, 0, 0); __builtin_amdgcn_s_setprio(0); } while (0)
; #define PG8_WAIT_L(n) asm volatile("s_waitcnt lgkmcnt(" #n ")" ::: "memory")
; #define PG8_BAR __builtin_amdgcn_s_barrier()
; #define PG8_SCHED __builtin_amdgcn_sched_barrier(0)
; template <class Epi>
; DI void gemm_phase(LAS unsigned char* lds, const Gemm g, const StaticOrder& S, const Epi& E) {
;     ...
;             PG8_LDB(B0, 0, 0); PG8_SCHED; PG8_LDA(At, 0, 0); PG8_STAGE(PG8_SA(1, 1), a1 + hstepA, voffA);
;             PG8_WAIT_L(8); PG8_BAR; PG8_WAIT_L(0); PG8_MMA(0, 0, At, B0); PG8_BAR; PG8_SCHED;
;             PG8_LDB(B1, 0, 1); PG8_STAGE(PG8_SB(0, 0), b2, voffB);
;             PG8_BAR; PG8_WAIT_L(0); PG8_MMA(0, 1, At, B1); PG8_BAR;
;             PG8_LDA(At, 0, 1); PG8_STAGE(PG8_SA(0, 0), a2, voffA);
;             PG8_BAR; PG8_WAIT_L(0); PG8_MMA(1, 0, At, B0); PG8_BAR; PG8_SCHED;
.LBB0_240:
	s_cmp_gt_i32 s70, 3
	s_cselect_b64 s[20:21], -1, 0
	s_and_b64 s[20:21], s[94:95], s[20:21]
	s_and_b64 s[20:21], s[20:21], exec
	s_cselect_b32 s11, 4, s86
	s_add_i32 s20, s11, -2
	s_add_u32 s21, s16, 0x100
	s_addc_u32 s44, s17, 0
	s_add_u32 s16, s18, 0x80
	s_addc_u32 s17, s19, 0
	s_mov_b32 s18, 0
	s_add_i32 s45, s18, 2
	s_add_u32 s37, s16, 0x80
	s_addc_u32 s19, s17, 0
	s_waitcnt lgkmcnt(0)
	s_add_i32 s46, 0, 0x10000
	v_add_u32_e32 v0, s46, v147
	ds_read_b128 v[130:133], v0
	ds_read_b128 v[148:151], v0 offset:1024
	ds_read_b128 v[152:155], v0 offset:2048
	ds_read_b128 v[156:159], v0 offset:3072
	s_cmp_eq_u32 s20, s18
	s_cselect_b32 s18, s12, s37
	s_cselect_b32 s19, s13, s19
	s_cselect_b32 s43, s15, s44
	s_cselect_b32 s42, s14, s21
	v_lshl_add_u64 v[204:205], s[16:17], 0, v[144:145]
	s_add_i32 m0, s89, 0xc000
	ds_read_b128 v[160:163], v186
	ds_read_b128 v[164:167], v186 offset:1024
	ds_read_b128 v[168:171], v186 offset:2048
	ds_read_b128 v[172:175], v186 offset:3072
	ds_read_b128 v[188:191], v186 offset:4096
	ds_read_b128 v[192:195], v186 offset:5120
	ds_read_b128 v[196:199], v186 offset:6144
	ds_read_b128 v[200:203], v186 offset:7168
	global_load_lds_dwordx4 v[204:205], off
	v_lshl_add_u64 v[204:205], s[16:17], 0, v[142:143]
	s_add_i32 m0, s89, 0xe000
	s_nop 0
	global_load_lds_dwordx4 v[204:205], off
	s_waitcnt lgkmcnt(8)
	s_barrier
	s_waitcnt lgkmcnt(0)
	s_setprio 1
	s_waitcnt lgkmcnt(0)
	v_mfma_f32_16x16x32_bf16 v[126:129], v[130:133], v[160:163], 0
	v_mfma_f32_16x16x32_bf16 v[122:125], v[152:155], v[160:163], 0
	v_mfma_f32_16x16x32_bf16 v[118:121], v[130:133], v[168:171], 0
	v_mfma_f32_16x16x32_bf16 v[114:117], v[152:155], v[168:171], 0
	v_mfma_f32_16x16x32_bf16 v[106:109], v[130:133], v[188:191], 0
	v_mfma_f32_16x16x32_bf16 v[98:101], v[152:155], v[188:191], 0
	v_mfma_f32_16x16x32_bf16 v[90:93], v[130:133], v[196:199], 0
	v_mfma_f32_16x16x32_bf16 v[82:85], v[152:155], v[196:199], 0
	v_mfma_f32_16x16x32_bf16 v[126:129], v[148:151], v[164:167], v[126:129]
	v_mfma_f32_16x16x32_bf16 v[122:125], v[156:159], v[164:167], v[122:125]
	v_mfma_f32_16x16x32_bf16 v[118:121], v[148:151], v[172:175], v[118:121]
	v_mfma_f32_16x16x32_bf16 v[114:117], v[156:159], v[172:175], v[114:117]
	v_mfma_f32_16x16x32_bf16 v[106:109], v[148:151], v[192:195], v[106:109]
	v_mfma_f32_16x16x32_bf16 v[98:101], v[156:159], v[192:195], v[98:101]
	v_mfma_f32_16x16x32_bf16 v[90:93], v[148:151], v[200:203], v[90:93]
	v_mfma_f32_16x16x32_bf16 v[82:85], v[156:159], v[200:203], v[82:85]
	s_setprio 0
	s_barrier
	s_add_i32 s37, 0, 0x14000
	s_add_i32 s46, s46, s88
	v_add_u32_e32 v0, s37, v147
	v_lshl_add_u64 v[220:221], s[42:43], 0, v[136:137]
	s_mov_b32 m0, s46
	ds_read_b128 v[204:207], v0
	ds_read_b128 v[208:211], v0 offset:1024
	ds_read_b128 v[212:215], v0 offset:2048
	ds_read_b128 v[216:219], v0 offset:3072
	global_load_lds_dwordx4 v[220:221], off
	v_lshl_add_u64 v[222:223], s[42:43], 0, v[140:141]
	s_add_i32 m0, s46, 0x2000
	s_nop 0
	global_load_lds_dwordx4 v[222:223], off
	s_barrier
	s_waitcnt lgkmcnt(0)
	s_setprio 1
	s_waitcnt lgkmcnt(0)
	v_mfma_f32_16x16x32_bf16 v[110:113], v[204:207], v[160:163], 0
	v_mfma_f32_16x16x32_bf16 v[102:105], v[212:215], v[160:163], 0
	v_mfma_f32_16x16x32_bf16 v[94:97], v[204:207], v[168:171], 0
	v_mfma_f32_16x16x32_bf16 v[86:89], v[212:215], v[168:171], 0
	v_mfma_f32_16x16x32_bf16 v[78:81], v[204:207], v[188:191], 0
	v_mfma_f32_16x16x32_bf16 v[74:77], v[212:215], v[188:191], 0
	v_mfma_f32_16x16x32_bf16 v[70:73], v[204:207], v[196:199], 0
	v_mfma_f32_16x16x32_bf16 v[66:69], v[212:215], v[196:199], 0
	v_mfma_f32_16x16x32_bf16 v[110:113], v[208:211], v[164:167], v[110:113]
	v_mfma_f32_16x16x32_bf16 v[102:105], v[216:219], v[164:167], v[102:105]
	v_mfma_f32_16x16x32_bf16 v[94:97], v[208:211], v[172:175], v[94:97]
	v_mfma_f32_16x16x32_bf16 v[86:89], v[216:219], v[172:175], v[86:89]
	v_mfma_f32_16x16x32_bf16 v[78:81], v[208:211], v[192:195], v[78:81]
	v_mfma_f32_16x16x32_bf16 v[74:77], v[216:219], v[192:195], v[74:77]
	v_mfma_f32_16x16x32_bf16 v[70:73], v[208:211], v[200:203], v[70:73]
	v_mfma_f32_16x16x32_bf16 v[66:69], v[216:219], v[200:203], v[66:69]
	s_setprio 0
	s_mov_b32 m0, s89
	v_lshl_add_u64 v[224:225], s[18:19], 0, v[134:135]
	s_barrier
	ds_read_b128 v[160:163], v186 offset:16384
	ds_read_b128 v[164:167], v186 offset:17408
	ds_read_b128 v[168:171], v186 offset:18432
	ds_read_b128 v[172:175], v186 offset:19456
	ds_read_b128 v[188:191], v186 offset:20480
	ds_read_b128 v[192:195], v186 offset:21504
	ds_read_b128 v[196:199], v186 offset:22528
	ds_read_b128 v[200:203], v186 offset:23552
	global_load_lds_dwordx4 v[224:225], off
	v_lshl_add_u64 v[226:227], s[18:19], 0, v[138:139]
	s_mov_b32 m0, s74
	s_nop 0
	global_load_lds_dwordx4 v[226:227], off
	s_barrier
	s_waitcnt lgkmcnt(0)
	s_setprio 1
	s_waitcnt lgkmcnt(0)
	v_mfma_f32_16x16x32_bf16 v[62:65], v[130:133], v[160:163], 0
	v_mfma_f32_16x16x32_bf16 v[58:61], v[152:155], v[160:163], 0
	v_mfma_f32_16x16x32_bf16 v[54:57], v[130:133], v[168:171], 0
	v_mfma_f32_16x16x32_bf16 v[50:53], v[152:155], v[168:171], 0
	v_mfma_f32_16x16x32_bf16 v[46:49], v[130:133], v[188:191], 0
	v_mfma_f32_16x16x32_bf16 v[38:41], v[152:155], v[188:191], 0
	v_mfma_f32_16x16x32_bf16 v[30:33], v[130:133], v[196:199], 0
	v_mfma_f32_16x16x32_bf16 v[22:25], v[152:155], v[196:199], 0
	v_mfma_f32_16x16x32_bf16 v[62:65], v[148:151], v[164:167], v[62:65]
	v_mfma_f32_16x16x32_bf16 v[58:61], v[156:159], v[164:167], v[58:61]
	v_mfma_f32_16x16x32_bf16 v[54:57], v[148:151], v[172:175], v[54:57]
	v_mfma_f32_16x16x32_bf16 v[50:53], v[156:159], v[172:175], v[50:53]
	v_mfma_f32_16x16x32_bf16 v[46:49], v[148:151], v[192:195], v[46:49]
	v_mfma_f32_16x16x32_bf16 v[38:41], v[156:159], v[192:195], v[38:41]
	v_mfma_f32_16x16x32_bf16 v[30:33], v[148:151], v[200:203], v[30:33]
	v_mfma_f32_16x16x32_bf16 v[22:25], v[156:159], v[200:203], v[22:25]
	s_setprio 0
	s_barrier
; #define PG8_STAGE(bufoff, gbase, voff) do { _Pragma("unroll") for (int _i = 0; _i < 2; ++_i) \
;         __builtin_amdgcn_global_load_lds((const unsigned*)((const char*)(gbase) + (voff)[_i]), (LAS unsigned*)(lds + (bufoff) + ldsw + _i * 8192), 16, 0, 0); } while (0)
; #define PG8_LDA(dst, b, h) do { _Pragma("unroll") for (int m = 0; m < 4; ++m) _Pragma("unroll") for (int k = 0; k < 2; ++k) dst[m][k] = *(const LAS bf16x8*)(lds + PG8_SA(b, h) + aoff + m * 2048 + k * 1024); } while (0)
; #define PG8_LDB(dst, b, h) do { _Pragma("unroll") for (int n = 0; n < 2; ++n) _Pragma("unroll") for (int k = 0; k < 2; ++k) dst[n][k] = *(const LAS bf16x8*)(lds + PG8_SB(b, h) + boff + n * 2048 + k * 1024); } while (0)
; #define PG8_MMA(ai, bj, At, Bt) do { __builtin_amdgcn_s_setprio(1); _Pragma("unroll") for (int m = 0; m < 4; ++m) _Pragma("unroll") for (int n = 0; n < 2; ++n) _Pragma("unroll") for (int k = 0; k < 2; ++k) \
;         acc[ai][bj][m][n] = __builtin_amdgcn_mfma_f32_16x16x32_bf16(Bt[n][k], At[m][k], acc[ai][bj][m][n], 0, 0, 0); __builtin_amdgcn_s_setprio(0); } while (0)
; #define PG8_WAIT_V(n) asm volatile("s_waitcnt vmcnt(" #n ")" ::: "memory")
; #define PG8_WAIT_L(n) asm volatile("s_waitcnt lgkmcnt(" #n ")" ::: "memory")
; #define PG8_BAR __builtin_amdgcn_s_barrier()
; #define PG8_SCHED __builtin_amdgcn_sched_barrier(0)
; template <class Epi>
; DI void gemm_phase(LAS unsigned char* lds, const Gemm g, const StaticOrder& S, const Epi& E) {
;     ...
;             PG8_STAGE(PG8_SB(0, 1), b2 + hstepB, voffB);
;             PG8_WAIT_V(6); PG8_BAR; PG8_MMA(1, 1, At, B1); PG8_BAR;
;             PG8_LDB(B0, 1, 0); PG8_SCHED; PG8_LDA(At, 1, 0); PG8_STAGE(PG8_SA(0, 1), a2 + hstepA, voffA);
;             PG8_WAIT_L(8); PG8_BAR; PG8_WAIT_L(0); PG8_MMA(0, 0, At, B0); PG8_BAR; PG8_SCHED;
;             PG8_LDB(B1, 1, 1); PG8_STAGE(PG8_SB(1, 0), b3, voffB);
	s_add_u32 s42, s42, s98
	s_addc_u32 s43, s43, 0
	s_add_i32 s37, s37, s88
	v_lshl_add_u64 v[228:229], s[42:43], 0, v[136:137]
	s_mov_b32 m0, s37
	v_lshl_add_u64 v[230:231], s[42:43], 0, v[140:141]
	global_load_lds_dwordx4 v[228:229], off
	s_add_i32 m0, s37, 0x2000
	s_nop 0
	global_load_lds_dwordx4 v[230:231], off
	s_waitcnt vmcnt(6)
	s_barrier
	s_setprio 1
	v_mfma_f32_16x16x32_bf16 v[42:45], v[204:207], v[160:163], 0
	v_mfma_f32_16x16x32_bf16 v[34:37], v[212:215], v[160:163], 0
	v_mfma_f32_16x16x32_bf16 v[26:29], v[204:207], v[168:171], 0
	v_mfma_f32_16x16x32_bf16 v[18:21], v[212:215], v[168:171], 0
	v_mfma_f32_16x16x32_bf16 v[14:17], v[204:207], v[188:191], 0
	v_mfma_f32_16x16x32_bf16 v[10:13], v[212:215], v[188:191], 0
	v_mfma_f32_16x16x32_bf16 v[6:9], v[204:207], v[196:199], 0
	v_mfma_f32_16x16x32_bf16 v[2:5], v[212:215], v[196:199], 0
	v_mfma_f32_16x16x32_bf16 v[42:45], v[208:211], v[164:167], v[42:45]
	v_mfma_f32_16x16x32_bf16 v[34:37], v[216:219], v[164:167], v[34:37]
	v_mfma_f32_16x16x32_bf16 v[26:29], v[208:211], v[172:175], v[26:29]
	v_mfma_f32_16x16x32_bf16 v[18:21], v[216:219], v[172:175], v[18:21]
	v_mfma_f32_16x16x32_bf16 v[14:17], v[208:211], v[192:195], v[14:17]
	v_mfma_f32_16x16x32_bf16 v[10:13], v[216:219], v[192:195], v[10:13]
	v_mfma_f32_16x16x32_bf16 v[6:9], v[208:211], v[200:203], v[6:9]
	v_mfma_f32_16x16x32_bf16 v[2:5], v[216:219], v[200:203], v[2:5]
	s_setprio 0
	s_add_i32 s37, 0, 0x18000
	v_add_u32_e32 v0, s37, v147
	s_barrier
	ds_read_b128 v[130:133], v0
	ds_read_b128 v[148:151], v0 offset:1024
	ds_read_b128 v[152:155], v0 offset:2048
	ds_read_b128 v[156:159], v0 offset:3072
	s_add_u32 s18, s18, s72
	s_addc_u32 s19, s19, 0
	s_mov_b32 m0, s75
	v_lshl_add_u64 v[204:205], s[18:19], 0, v[134:135]
	ds_read_b128 v[160:163], v186 offset:32768
	ds_read_b128 v[164:167], v186 offset:33792
	ds_read_b128 v[168:171], v186 offset:34816
	ds_read_b128 v[172:175], v186 offset:35840
	ds_read_b128 v[188:191], v186 offset:36864
	ds_read_b128 v[192:195], v186 offset:37888
	ds_read_b128 v[196:199], v186 offset:38912
	ds_read_b128 v[200:203], v186 offset:39936
	global_load_lds_dwordx4 v[204:205], off
	v_lshl_add_u64 v[204:205], s[18:19], 0, v[138:139]
	s_mov_b32 m0, s3
	s_nop 0
	global_load_lds_dwordx4 v[204:205], off
	s_waitcnt lgkmcnt(8)
	s_barrier
	s_waitcnt lgkmcnt(0)
	s_setprio 1
	s_waitcnt lgkmcnt(0)
	v_mfma_f32_16x16x32_bf16 v[126:129], v[130:133], v[160:163], v[126:129]
	v_mfma_f32_16x16x32_bf16 v[122:125], v[152:155], v[160:163], v[122:125]
	v_mfma_f32_16x16x32_bf16 v[118:121], v[130:133], v[168:171], v[118:121]
	v_mfma_f32_16x16x32_bf16 v[114:117], v[152:155], v[168:171], v[114:117]
	v_mfma_f32_16x16x32_bf16 v[106:109], v[130:133], v[188:191], v[106:109]
	v_mfma_f32_16x16x32_bf16 v[98:101], v[152:155], v[188:191], v[98:101]
	v_mfma_f32_16x16x32_bf16 v[90:93], v[130:133], v[196:199], v[90:93]
	v_mfma_f32_16x16x32_bf16 v[82:85], v[152:155], v[196:199], v[82:85]
	v_mfma_f32_16x16x32_bf16 v[126:129], v[148:151], v[164:167], v[126:129]
	v_mfma_f32_16x16x32_bf16 v[122:125], v[156:159], v[164:167], v[122:125]
	v_mfma_f32_16x16x32_bf16 v[118:121], v[148:151], v[172:175], v[118:121]
	v_mfma_f32_16x16x32_bf16 v[114:117], v[156:159], v[172:175], v[114:117]
	v_mfma_f32_16x16x32_bf16 v[106:109], v[148:151], v[192:195], v[106:109]
	v_mfma_f32_16x16x32_bf16 v[98:101], v[156:159], v[192:195], v[98:101]
	v_mfma_f32_16x16x32_bf16 v[90:93], v[148:151], v[200:203], v[90:93]
	v_mfma_f32_16x16x32_bf16 v[82:85], v[156:159], v[200:203], v[82:85]
	s_setprio 0
	s_barrier
	s_add_i32 s18, 0, 0x1c000
	s_add_i32 s19, s37, s88
	v_add_u32_e32 v0, s18, v147
	v_lshl_add_u64 v[220:221], v[220:221], 0, s[82:83]
	s_mov_b32 m0, s19
	ds_read_b128 v[204:207], v0
	ds_read_b128 v[208:211], v0 offset:1024
	ds_read_b128 v[212:215], v0 offset:2048
	ds_read_b128 v[216:219], v0 offset:3072
	global_load_lds_dwordx4 v[220:221], off
	v_lshl_add_u64 v[220:221], v[222:223], 0, s[82:83]
	s_add_i32 m0, s19, 0x2000
	s_nop 0
	global_load_lds_dwordx4 v[220:221], off
	s_barrier
; #define PG8_STAGE(bufoff, gbase, voff) do { _Pragma("unroll") for (int _i = 0; _i < 2; ++_i) \
;         __builtin_amdgcn_global_load_lds((const unsigned*)((const char*)(gbase) + (voff)[_i]), (LAS unsigned*)(lds + (bufoff) + ldsw + _i * 8192), 16, 0, 0); } while (0)
; #define PG8_LDA(dst, b, h) do { _Pragma("unroll") for (int m = 0; m < 4; ++m) _Pragma("unroll") for (int k = 0; k < 2; ++k) dst[m][k] = *(const LAS bf16x8*)(lds + PG8_SA(b, h) + aoff + m * 2048 + k * 1024); } while (0)
; #define PG8_MMA(ai, bj, At, Bt) do { __builtin_amdgcn_s_setprio(1); _Pragma("unroll") for (int m = 0; m < 4; ++m) _Pragma("unroll") for (int n = 0; n < 2; ++n) _Pragma("unroll") for (int k = 0; k < 2; ++k) \
;         acc[ai][bj][m][n] = __builtin_amdgcn_mfma_f32_16x16x32_bf16(Bt[n][k], At[m][k], acc[ai][bj][m][n], 0, 0, 0); __builtin_amdgcn_s_setprio(0); } while (0)
; #define PG8_WAIT_V(n) asm volatile("s_waitcnt vmcnt(" #n ")" ::: "memory")
; #define PG8_WAIT_L(n) asm volatile("s_waitcnt lgkmcnt(" #n ")" ::: "memory")
; #define PG8_BAR __builtin_amdgcn_s_barrier()
; #define PG8_SCHED __builtin_amdgcn_sched_barrier(0)
; template <class Epi>
; DI void gemm_phase(LAS unsigned char* lds, const Gemm g, const StaticOrder& S, const Epi& E) {
;     ...
;             PG8_BAR; PG8_WAIT_L(0); PG8_MMA(0, 1, At, B1); PG8_BAR;
;             PG8_LDA(At, 1, 1); PG8_STAGE(PG8_SA(1, 0), a3, voffA);
;             PG8_BAR; PG8_WAIT_L(0); PG8_MMA(1, 0, At, B0); PG8_BAR; PG8_SCHED;
;             PG8_STAGE(PG8_SB(1, 1), b3 + hstepB, voffB);
;             PG8_WAIT_V(6); PG8_BAR; PG8_MMA(1, 1, At, B1); PG8_BAR;
;         }
	s_waitcnt lgkmcnt(0)
	s_setprio 1
	s_waitcnt lgkmcnt(0)
	v_mfma_f32_16x16x32_bf16 v[110:113], v[204:207], v[160:163], v[110:113]
	v_mfma_f32_16x16x32_bf16 v[102:105], v[212:215], v[160:163], v[102:105]
	v_mfma_f32_16x16x32_bf16 v[94:97], v[204:207], v[168:171], v[94:97]
	v_mfma_f32_16x16x32_bf16 v[86:89], v[212:215], v[168:171], v[86:89]
	v_mfma_f32_16x16x32_bf16 v[78:81], v[204:207], v[188:191], v[78:81]
	v_mfma_f32_16x16x32_bf16 v[74:77], v[212:215], v[188:191], v[74:77]
	v_mfma_f32_16x16x32_bf16 v[70:73], v[204:207], v[196:199], v[70:73]
	v_mfma_f32_16x16x32_bf16 v[66:69], v[212:215], v[196:199], v[66:69]
	v_mfma_f32_16x16x32_bf16 v[110:113], v[208:211], v[164:167], v[110:113]
	v_mfma_f32_16x16x32_bf16 v[102:105], v[216:219], v[164:167], v[102:105]
	v_mfma_f32_16x16x32_bf16 v[94:97], v[208:211], v[172:175], v[94:97]
	v_mfma_f32_16x16x32_bf16 v[86:89], v[216:219], v[172:175], v[86:89]
	v_mfma_f32_16x16x32_bf16 v[78:81], v[208:211], v[192:195], v[78:81]
	v_mfma_f32_16x16x32_bf16 v[74:77], v[216:219], v[192:195], v[74:77]
	v_mfma_f32_16x16x32_bf16 v[70:73], v[208:211], v[200:203], v[70:73]
	v_mfma_f32_16x16x32_bf16 v[66:69], v[216:219], v[200:203], v[66:69]
	s_setprio 0
	s_mov_b32 m0, s24
	v_lshl_add_u64 v[220:221], v[224:225], 0, s[82:83]
	s_barrier
	ds_read_b128 v[160:163], v186 offset:49152
	ds_read_b128 v[164:167], v186 offset:50176
	ds_read_b128 v[168:171], v186 offset:51200
	ds_read_b128 v[172:175], v186 offset:52224
	ds_read_b128 v[188:191], v186 offset:53248
	ds_read_b128 v[192:195], v186 offset:54272
	ds_read_b128 v[196:199], v186 offset:55296
	ds_read_b128 v[200:203], v186 offset:56320
	global_load_lds_dwordx4 v[220:221], off
	v_lshl_add_u64 v[220:221], v[226:227], 0, s[82:83]
	s_mov_b32 m0, s97
	s_nop 0
	global_load_lds_dwordx4 v[220:221], off
	s_barrier
	s_waitcnt lgkmcnt(0)
	s_setprio 1
	s_waitcnt lgkmcnt(0)
	v_mfma_f32_16x16x32_bf16 v[62:65], v[130:133], v[160:163], v[62:65]
	v_mfma_f32_16x16x32_bf16 v[58:61], v[152:155], v[160:163], v[58:61]
	v_mfma_f32_16x16x32_bf16 v[54:57], v[130:133], v[168:171], v[54:57]
	v_mfma_f32_16x16x32_bf16 v[50:53], v[152:155], v[168:171], v[50:53]
	v_mfma_f32_16x16x32_bf16 v[46:49], v[130:133], v[188:191], v[46:49]
	v_mfma_f32_16x16x32_bf16 v[38:41], v[152:155], v[188:191], v[38:41]
	v_mfma_f32_16x16x32_bf16 v[30:33], v[130:133], v[196:199], v[30:33]
	v_mfma_f32_16x16x32_bf16 v[22:25], v[152:155], v[196:199], v[22:25]
	v_mfma_f32_16x16x32_bf16 v[62:65], v[148:151], v[164:167], v[62:65]
	v_mfma_f32_16x16x32_bf16 v[58:61], v[156:159], v[164:167], v[58:61]
	v_mfma_f32_16x16x32_bf16 v[54:57], v[148:151], v[172:175], v[54:57]
	v_mfma_f32_16x16x32_bf16 v[50:53], v[156:159], v[172:175], v[50:53]
	v_mfma_f32_16x16x32_bf16 v[46:49], v[148:151], v[192:195], v[46:49]
	v_mfma_f32_16x16x32_bf16 v[38:41], v[156:159], v[192:195], v[38:41]
	v_mfma_f32_16x16x32_bf16 v[30:33], v[148:151], v[200:203], v[30:33]
	v_mfma_f32_16x16x32_bf16 v[22:25], v[156:159], v[200:203], v[22:25]
	s_setprio 0
	s_barrier
	s_add_i32 s18, s18, s88
	v_lshl_add_u64 v[130:131], v[228:229], 0, s[82:83]
	s_mov_b32 m0, s18
	s_nop 0
	global_load_lds_dwordx4 v[130:131], off
	v_lshl_add_u64 v[130:131], v[230:231], 0, s[82:83]
	s_add_i32 m0, s18, 0x2000
	s_nop 0
	global_load_lds_dwordx4 v[130:131], off
	s_waitcnt vmcnt(6)
	s_barrier
	s_setprio 1
	v_mfma_f32_16x16x32_bf16 v[42:45], v[204:207], v[160:163], v[42:45]
	v_mfma_f32_16x16x32_bf16 v[34:37], v[212:215], v[160:163], v[34:37]
	v_mfma_f32_16x16x32_bf16 v[26:29], v[204:207], v[168:171], v[26:29]
	v_mfma_f32_16x16x32_bf16 v[18:21], v[212:215], v[168:171], v[18:21]
	v_mfma_f32_16x16x32_bf16 v[14:17], v[204:207], v[188:191], v[14:17]
	v_mfma_f32_16x16x32_bf16 v[10:13], v[212:215], v[188:191], v[10:13]
	v_mfma_f32_16x16x32_bf16 v[6:9], v[204:207], v[196:199], v[6:9]
	v_mfma_f32_16x16x32_bf16 v[2:5], v[212:215], v[196:199], v[2:5]
	v_mfma_f32_16x16x32_bf16 v[42:45], v[208:211], v[164:167], v[42:45]
	v_mfma_f32_16x16x32_bf16 v[34:37], v[216:219], v[164:167], v[34:37]
	v_mfma_f32_16x16x32_bf16 v[26:29], v[208:211], v[172:175], v[26:29]
	v_mfma_f32_16x16x32_bf16 v[18:21], v[216:219], v[172:175], v[18:21]
	v_mfma_f32_16x16x32_bf16 v[14:17], v[208:211], v[192:195], v[14:17]
	v_mfma_f32_16x16x32_bf16 v[10:13], v[216:219], v[192:195], v[10:13]
	v_mfma_f32_16x16x32_bf16 v[6:9], v[208:211], v[200:203], v[6:9]
	v_mfma_f32_16x16x32_bf16 v[2:5], v[216:219], v[200:203], v[2:5]
	s_setprio 0
	s_add_u32 s21, s21, 0x100
	s_addc_u32 s44, s44, 0
	s_add_u32 s16, s16, 0x100
	s_addc_u32 s17, s17, 0
	s_cmp_ge_u32 s45, s11
	s_mov_b32 s18, s45
	s_barrier
	s_cbranch_scc1 .Lk_loop_exit
	.p2align 6
